# attention PV: first V transpose-read group issued early; alignment pads keep GEMM/attention loop heads at baseline byte phase
# baseline (speedup 1.0000x reference)
; #define PG8_STAGE(bufoff, gbase, voff) do { _Pragma("unroll") for (int _i = 0; _i < 2; ++_i) \
;         __builtin_amdgcn_global_load_lds((const unsigned*)((const char*)(gbase) + (voff)[_i]), (PG8_LAS unsigned*)(lds + (bufoff) + ldsw + _i * 8192), 16, 0, 0); } while (0)
; #define PG8_WAIT_V(n) asm volatile("s_waitcnt vmcnt(" #n ")" ::: "memory")
; #define PG8_BAR __builtin_amdgcn_s_barrier()
; template <class Epi, class Sched, bool ALIGN_EPI = false, bool SP2 = false>
; __device__ __forceinline__ void gemm_phase(PG8_LAS unsigned char* lds, const Gemm g, const Sched& S, const Epi& E) {
;     int tid_ = threadIdx.x; asm volatile("" : "+v"(tid_));
;     const int tid = tid_, wid = __builtin_amdgcn_readfirstlane(tid >> 6), lane = tid & 63, wr = wid >> 2, wc = wid & 3, fr = lane & 15, fq = lane >> 4;
;     const int K = g.K, nt = K / BK;
;     unsigned voffA[2], voffB[2];
; #pragma unroll
;     for (int i = 0; i < 2; ++i) { int R, C; stage_rc(tid * 16 + i * 8192, R, C); const int Rb = Epi::PERM ? ((R & ~31) + perm32(R & 31)) : R;
;         voffA[i] = (unsigned)(R * K + C) * 2u; voffB[i] = (unsigned)(Rb * K + C) * 2u; }
;     const size_t kstep = (size_t)(BK * 2);
;     const size_t hstep = (size_t)HALF * K * 2;
;     const size_t tstep = 2 * hstep;
;     const unsigned ldsw = (unsigned)wid * 1024u;
;     const int aoff = lds_byte(wr * 64 + fr, fq * 8), boff = lds_byte(wc * 32 + fr, fq * 8);
;     ...
;     Unit cur, nxt; int ui = 0;
;     if (!S.next(0, cur)) return;
;     f32x4 acc[2][2][4][2];
; #pragma unroll
;     for (int a = 0; a < 2; ++a)
; #pragma unroll
;         for (int b = 0; b < 2; ++b)
; #pragma unroll
;             for (int m = 0; m < 4; ++m)
; #pragma unroll
;                 for (int n = 0; n < 2; ++n) acc[a][b][m][n] = (f32x4){0.f, 0.f, 0.f, 0.f};
;     bf16x8 At[4][2], B0[2][2], B1[2][2];
;     const char* cA = (const char*)g.A + (size_t)cur.pm * tstep; const char* cB = (const char*)g.Bt + (size_t)cur.pn * tstep;
;     S.a_ready(cur);
;     if constexpr (SP2) {
;         PG8_STAGE(PG8_SB(0, 0), cB, voffB); PG8_STAGE(PG8_SB(0, 1), cB + hstep, voffB); PG8_STAGE(PG8_SA(0, 0), cA, voffA); PG8_STAGE(PG8_SA(0, 1), cA + hstep, voffA);
;         if (wr == 1) PG8_BAR;
;         PG8_WAIT_V(2); PG8_BAR;
;         PG8_STAGE(PG8_SB(1, 0), cB + kstep, voffB); PG8_STAGE(PG8_SA(1, 0), cA + kstep, voffA); PG8_STAGE(PG8_SB(1, 1), cB + hstep + kstep, voffB);
.LBB0_162:
	s_or_b64 exec, exec, s[14:15]
	s_nop 0
	s_nop 0
	s_nop 0
	s_nop 0
	s_nop 0
	s_nop 0
	s_nop 0
	s_nop 0
	s_nop 0
	s_nop 0
	v_writelane_b32 v254, s34, 49
	s_ashr_i32 s3, s46, 31
	s_ashr_i32 s33, s2, 31
	s_mov_b64 s[24:25], s[0:1]
	s_mov_b64 s[26:27], s[0:1]
	s_mov_b64 s[14:15], s[0:1]
	s_mov_b64 s[16:17], s[0:1]
	s_mov_b64 s[18:19], s[0:1]
	s_mov_b64 s[20:21], s[0:1]
	s_mov_b64 s[22:23], s[0:1]
	v_mov_b32_e32 v14, v216
	v_writelane_b32 v254, s35, 50
	s_waitcnt lgkmcnt(0)
	s_barrier
	s_cmpk_gt_i32 s2, 0x11ff
	v_writelane_b32 v254, s60, 51
	v_readfirstlane_b32 s30, v14
	s_nop 0
	v_writelane_b32 v254, s61, 52
	s_cbranch_scc1 .LBB0_186
	v_lshlrev_b32_e32 v0, 4, v14
	v_add_u32_e32 v1, 0x2000, v0
	v_ashrrev_i32_e32 v2, 31, v1
	v_lshrrev_b32_e32 v2, 22, v2
	v_add_u32_e32 v2, v1, v2
	v_ashrrev_i32_e32 v8, 10, v2
	v_mul_i32_i24_e32 v2, 0x400, v8
	v_sub_u32_e32 v1, v1, v2
	v_lshrrev_b32_e32 v2, 4, v1
	v_bitop3_b32 v1, v2, v1, 32 bitop3:0x6c
	v_ashrrev_i32_e32 v2, 31, v1
	s_load_dwordx2 s[24:25], s[24:25], 0xc8
	s_nop 0
	s_load_dwordx2 s[26:27], s[26:27], 0xc8
	v_lshrrev_b32_e32 v2, 26, v2
	v_add_u32_e32 v2, v1, v2
	v_lshlrev_b32_e32 v3, 3, v8
	v_ashrrev_i32_e32 v9, 6, v2
	v_and_b32_e32 v3, -16, v3
	v_add_u32_e32 v3, v9, v3
	s_waitcnt lgkmcnt(0)
	s_add_u32 s13, s24, 0x7800000
	v_and_b32_e32 v4, 3, v9
	s_mov_b32 s24, 0xfffe0
	v_lshrrev_b32_e32 v5, 2, v3
	v_lshlrev_b32_e32 v6, 1, v3
	v_and_b32_e32 v2, 0xc0, v2
	v_and_or_b32 v4, v3, s24, v4
	v_and_b32_e32 v5, 4, v5
	v_and_b32_e32 v6, 24, v6
	v_sub_u32_e32 v1, v1, v2
	v_mov_b32_e32 v2, 1
	v_or3_b32 v4, v4, v5, v6
	v_lshlrev_b32_e32 v5, 5, v8
	v_ashrrev_i16_sdwa v1, v2, sext(v1) dst_sel:DWORD dst_unused:UNUSED_PAD src0_sel:DWORD src1_sel:BYTE_0
	v_and_b32_e32 v5, 32, v5
	v_bfe_i32 v10, v1, 0, 16
	v_add_lshl_u32 v1, v5, v10, 1
	v_lshl_add_u32 v144, v4, 12, v1
	v_lshl_add_u32 v146, v3, 12, v1
	v_bfe_i32 v1, v14, 27, 1
	v_lshrrev_b32_e32 v1, 22, v1
	v_add_u32_e32 v1, v0, v1
	v_and_b32_e32 v1, 0xfffffc00, v1
	v_sub_u32_e32 v0, v0, v1
	v_lshrrev_b32_e32 v1, 4, v0
	v_ashrrev_i32_e32 v3, 31, v14
	v_bitop3_b32 v0, v1, v0, 32 bitop3:0x6c
	v_lshrrev_b32_e32 v3, 26, v3
	v_ashrrev_i32_e32 v1, 31, v0
	v_add_u32_e32 v3, v14, v3
	v_lshrrev_b32_e32 v1, 26, v1
	v_ashrrev_i32_e32 v12, 6, v3
	v_add_u32_e32 v1, v0, v1
	v_lshlrev_b32_e32 v3, 3, v12
	s_addc_u32 s47, s25, 0
	v_ashrrev_i32_e32 v11, 6, v1
	v_and_b32_e32 v3, -16, v3
	s_add_u32 s48, s26, 0x200000
	v_add_u32_e32 v3, v11, v3
	v_and_b32_e32 v4, 3, v11
	s_addc_u32 s49, s27, 0
	v_and_or_b32 v4, v3, s24, v4
	s_lshr_b32 s24, s33, 29
	s_add_i32 s24, s2, s24
	s_ashr_i32 s25, s30, 6
	s_ashr_i32 s26, s24, 3
	s_and_b32 s24, s24, -8
	s_ashr_i32 s31, s30, 8
	s_lshl_b32 s50, s25, 10
	s_sub_i32 s24, s2, s24
	s_cmp_lt_i32 s24, 0
	s_movk_i32 s51, 0x241
	s_cselect_b32 s27, s51, 0x240
	s_mul_i32 s24, s24, s27
	s_add_i32 s24, s24, s26
	s_mul_hi_i32 s26, s24, 0x38e38e39
	s_lshr_b32 s27, s26, 31
	s_ashr_i32 s26, s26, 5
	s_add_i32 s26, s26, s27
	s_lshl_b32 s27, s26, 2
	s_mulk_i32 s26, 0x90
	s_sub_i32 s26, s24, s26
	s_sext_i32_i16 s24, s26
	s_bfe_u32 s24, s24, 0x2001d
	s_add_i32 s28, s26, s24
	s_sext_i32_i16 s24, s28
	s_and_b32 s28, s28, 0xfffc
	s_sub_i32 s26, s26, s28
	s_sext_i32_i16 s26, s26
	v_lshrrev_b32_e32 v5, 2, v3
	v_lshlrev_b32_e32 v6, 1, v3
	v_and_b32_e32 v1, 0xc0, v1
	s_lshr_b32 s24, s24, 2
	s_add_i32 s36, s27, s26
	v_and_b32_e32 v5, 4, v5
	v_and_b32_e32 v6, 24, v6
	v_sub_u32_e32 v0, v0, v1
	s_ashr_i32 s37, s36, 31
	s_bfe_i64 s[28:29], s[24:25], 0x100000
	v_or3_b32 v4, v4, v5, v6
	v_lshlrev_b32_e32 v5, 5, v12
	v_ashrrev_i16_sdwa v0, v2, sext(v0) dst_sel:DWORD dst_unused:UNUSED_PAD src0_sel:DWORD src1_sel:BYTE_0
	s_lshl_b64 s[26:27], s[36:37], 20
	s_lshl_b64 s[28:29], s[28:29], 20
	v_and_b32_e32 v5, 32, v5
	v_bfe_i32 v13, v0, 0, 16
	s_add_u32 s42, s48, s28
	v_add_lshl_u32 v0, v5, v13, 1
	s_addc_u32 s43, s49, s29
	s_add_i32 s52, s50, 0
	v_lshl_add_u32 v148, v4, 12, v0
	s_add_i32 m0, s52, 0x10000
	v_lshl_add_u32 v150, v3, 12, v0
	global_load_lds_dwordx4 v148, s[42:43]
	s_add_i32 m0, s52, 0x12000
	s_add_u32 s28, s42, 0x80000
	global_load_lds_dwordx4 v144, s[42:43]
	s_addc_u32 s29, s43, 0
	s_add_i32 m0, s52, 0x14000
	v_mov_b32_e32 v153, 0
	global_load_lds_dwordx4 v148, s[28:29]
	s_add_i32 m0, s52, 0x16000
	s_add_u32 s40, s13, s26
	s_addc_u32 s41, s47, s27
	s_add_i32 s53, s52, 0x2000
	global_load_lds_dwordx4 v144, s[28:29]
	s_mov_b32 m0, s52
	s_add_u32 s26, s40, 0x80000
	global_load_lds_dwordx4 v150, s[40:41]
	s_mov_b32 m0, s53
	s_addc_u32 s27, s41, 0
	s_add_i32 s54, s52, 0x4000
	global_load_lds_dwordx4 v146, s[40:41]
	s_mov_b32 m0, s54
	s_add_i32 s55, s52, 0x6000
	global_load_lds_dwordx4 v150, s[26:27]
	s_mov_b32 m0, s55
	v_mov_b32_e32 v149, v153
	global_load_lds_dwordx4 v146, s[26:27]
	s_load_dwordx2 s[28:29], s[14:15], 0xc8
	s_nop 0
	s_load_dwordx2 s[14:15], s[16:17], 0xc8
	s_load_dwordx2 s[26:27], s[18:19], 0xc8
	s_nop 0
	s_load_dwordx2 s[20:21], s[20:21], 0xc8
	s_nop 0
	s_load_dwordx2 s[16:17], s[22:23], 0x98
	v_mov_b32_e32 v145, v153
	v_mov_b32_e32 v151, v153
	v_mov_b32_e32 v147, v153
	s_cmp_eq_u32 s31, 1
	v_lshl_add_u64 v[6:7], s[42:43], 0, v[148:149]
	v_lshl_add_u64 v[2:3], s[42:43], 0, v[144:145]
	v_lshl_add_u64 v[0:1], s[40:41], 0, v[150:151]
	s_cselect_b64 s[18:19], -1, 0
	s_cmp_lg_u32 s31, 1
	v_lshl_add_u64 v[4:5], s[40:41], 0, v[146:147]
	s_cbranch_scc1 .LBB0_165
	s_barrier

; __device__ __forceinline__ void finishSM(f32x16& p0, f32x16& p1, float alpha, float& l_reg, bf16x8& pa0, bf16x8& pa1, bf16x8& pa2, bf16x8& pa3) {
;     for (int r = 0; r < 16; ++r) p1[r] = __builtin_amdgcn_exp2f(p1[r]);
;     float ps = 0; for (int r = 0; r < 16; ++r) ps += p0[r]; for (int r = 0; r < 16; ++r) ps += p1[r];
;     { auto rr = __builtin_amdgcn_permlane32_swap(__float_as_uint(ps), __float_as_uint(ps), false, false);
;       ps = __uint_as_float(rr[0]) + __uint_as_float(rr[1]); }
;     l_reg = l_reg * alpha + ps;
;     ...
;     PK4(p0, 0, pa0); PK4(p0, 8, pa1); PK4(p1, 0, pa2); PK4(p1, 8, pa3);
;     ...
; }
; template <int KB>
; __device__ __forceinline__ void qkt(f32x16& p0, f32x16& p1, const char* K_lds, int r32, int hi, const bf16x8* qr) {
;     p0 = f32x16{}; p1 = f32x16{};
;     const char* kb[4];
; #pragma unroll
;     for (int dd = 0; dd < 4; ++dd) kb[dd] = K_lds + KB * SHM_K + KSWZ(r32, (dd * 16 + hi * 8) * 2);
; #pragma unroll
;     for (int d0 = 0; d0 < 8; ++d0) { const char* a = kb[d0 & 3] + (d0 >> 2) * 128;
;         bf16x8 b0 = *reinterpret_cast<const bf16x8*>(a);
;         bf16x8 b1 = *reinterpret_cast<const bf16x8*>(a + 32 * 256);
;         p0 = __builtin_amdgcn_mfma_f32_32x32x16_bf16(b0, qr[d0], p0, 0, 0, 0);
;         p1 = __builtin_amdgcn_mfma_f32_32x32x16_bf16(b1, qr[d0], p1, 0, 0, 0); }
; }
; template <int VB>
; __device__ __forceinline__ void pv_tile(f32x16* o, int vb0, bf16x8 pa0, bf16x8 pa1, bf16x8 pa2, bf16x8 pa3) {
;     ...
;     PV_D0(0); PV_D0(1); PV_D0(2); PV_D0(3);
.LBB0_320:
	ds_read_b128 v[64:67], v201 offset:49152
	ds_read_b128 v[68:71], v201 offset:57344
	ds_read_b128 v[96:99], v230 offset:49152
	ds_read_b128 v[100:103], v230 offset:57344
	v_exp_f32_e32 v104, v126
	v_exp_f32_e32 v105, v127
	s_waitcnt lgkmcnt(3)
	v_mfma_f32_32x32x16_bf16 v[80:95], v[64:67], v[156:159], 0
	v_exp_f32_e32 v106, v122
	v_exp_f32_e32 v107, v123
	v_exp_f32_e32 v108, v118
	v_exp_f32_e32 v109, v119
	v_exp_f32_e32 v110, v116
	v_exp_f32_e32 v111, v117
	v_exp_f32_e32 v112, v112
	s_waitcnt lgkmcnt(2)
	v_mfma_f32_32x32x16_bf16 v[64:79], v[68:71], v[156:159], 0
	v_exp_f32_e32 v113, v113
	v_exp_f32_e32 v116, v124
	v_exp_f32_e32 v117, v125
	v_exp_f32_e32 v118, v120
	v_exp_f32_e32 v119, v121
	v_exp_f32_e32 v114, v114
	v_exp_f32_e32 v115, v115
	s_waitcnt lgkmcnt(1)
	v_mfma_f32_32x32x16_bf16 v[80:95], v[96:99], v[152:155], v[80:95]
	s_waitcnt lgkmcnt(0)
	v_mfma_f32_32x32x16_bf16 v[64:79], v[100:103], v[152:155], v[64:79]
	ds_read_b128 v[96:99], v229 offset:49152
	ds_read_b128 v[100:103], v229 offset:57344
	s_waitcnt lgkmcnt(1)
	v_mfma_f32_32x32x16_bf16 v[80:95], v[96:99], v[148:151], v[80:95]
	s_waitcnt lgkmcnt(0)
	v_mfma_f32_32x32x16_bf16 v[64:79], v[100:103], v[148:151], v[64:79]
	ds_read_b128 v[96:99], v207 offset:49152
	ds_read_b128 v[100:103], v207 offset:57344
	s_waitcnt lgkmcnt(1)
	v_mfma_f32_32x32x16_bf16 v[80:95], v[96:99], v[144:147], v[80:95]
	s_waitcnt lgkmcnt(0)
	v_mfma_f32_32x32x16_bf16 v[64:79], v[100:103], v[144:147], v[64:79]
	ds_read_b128 v[96:99], v201 offset:49280
	ds_read_b128 v[100:103], v201 offset:57472
	s_waitcnt lgkmcnt(1)
	v_mfma_f32_32x32x16_bf16 v[80:95], v[96:99], v[140:143], v[80:95]
	s_waitcnt lgkmcnt(0)
	v_mfma_f32_32x32x16_bf16 v[64:79], v[100:103], v[140:143], v[64:79]
	ds_read_b128 v[96:99], v230 offset:49280
	ds_read_b128 v[100:103], v230 offset:57472
	s_waitcnt lgkmcnt(1)
	v_mfma_f32_32x32x16_bf16 v[80:95], v[96:99], v[136:139], v[80:95]
	s_waitcnt lgkmcnt(0)
	v_mfma_f32_32x32x16_bf16 v[64:79], v[100:103], v[136:139], v[64:79]
	ds_read_b128 v[96:99], v229 offset:49280
	ds_read_b128 v[100:103], v229 offset:57472
	s_waitcnt lgkmcnt(1)
	v_mfma_f32_32x32x16_bf16 v[80:95], v[96:99], v[132:135], v[80:95]
	s_waitcnt lgkmcnt(0)
	v_mfma_f32_32x32x16_bf16 v[64:79], v[100:103], v[132:135], v[64:79]
	ds_read_b128 v[96:99], v207 offset:49280
	ds_read_b128 v[100:103], v207 offset:57472
	ds_read_b64_tr_b16 v[238:239], v225 offset:0
	ds_read_b64_tr_b16 v[240:241], v225 offset:0x800
	ds_read_b64_tr_b16 v[242:243], v225 offset:0x1000
	ds_read_b64_tr_b16 v[244:245], v225 offset:0x1800
	ds_read_b64_tr_b16 v[246:247], v225 offset:0x2000
	ds_read_b64_tr_b16 v[248:249], v225 offset:0x2800
	ds_read_b64_tr_b16 v[250:251], v225 offset:0x3000
	ds_read_b64_tr_b16 v[252:253], v225 offset:0x3800
	s_waitcnt lgkmcnt(9)
	v_mfma_f32_32x32x16_bf16 v[80:95], v[96:99], v[128:131], v[80:95]
	v_add_f32_e32 v96, 0, v169
	v_add_f32_e32 v96, v170, v96
	v_add_f32_e32 v96, v171, v96
	v_add_f32_e32 v96, v173, v96
	v_add_f32_e32 v96, v174, v96
	v_add_f32_e32 v96, v177, v96
	v_add_f32_e32 v96, v172, v96
	v_add_f32_e32 v96, v175, v96
	v_add_f32_e32 v96, v161, v96
	v_add_f32_e32 v96, v163, v96
	v_add_f32_e32 v96, v164, v96
	v_add_f32_e32 v96, v167, v96
	v_add_f32_e32 v96, v162, v96
	v_add_f32_e32 v96, v165, v96
	v_add_f32_e32 v96, v166, v96
	v_add_f32_e32 v96, v168, v96
	v_add_f32_e32 v96, v104, v96
	v_add_f32_e32 v96, v105, v96
	v_add_f32_e32 v96, v106, v96
	v_add_f32_e32 v96, v107, v96
	v_add_f32_e32 v96, v108, v96
	v_add_f32_e32 v96, v109, v96
	v_add_f32_e32 v96, v110, v96
	v_add_f32_e32 v96, v111, v96
	v_add_f32_e32 v96, v112, v96
	v_add_f32_e32 v96, v113, v96
	s_waitcnt lgkmcnt(8)
; __device__ __forceinline__ void finishSM(f32x16& p0, f32x16& p1, float alpha, float& l_reg, bf16x8& pa0, bf16x8& pa1, bf16x8& pa2, bf16x8& pa3) {
;     for (int r = 0; r < 16; ++r) p1[r] = __builtin_amdgcn_exp2f(p1[r]);
;     float ps = 0; for (int r = 0; r < 16; ++r) ps += p0[r]; for (int r = 0; r < 16; ++r) ps += p1[r];
;     { auto rr = __builtin_amdgcn_permlane32_swap(__float_as_uint(ps), __float_as_uint(ps), false, false);
;       ps = __uint_as_float(rr[0]) + __uint_as_float(rr[1]); }
;     l_reg = l_reg * alpha + ps;
;     ...
;     PK4(p0, 0, pa0); PK4(p0, 8, pa1); PK4(p1, 0, pa2); PK4(p1, 8, pa3);
;     ...
; }
; template <int KB>
; __device__ __forceinline__ void qkt(f32x16& p0, f32x16& p1, const char* K_lds, int r32, int hi, const bf16x8* qr) {
;     p0 = f32x16{}; p1 = f32x16{};
;     const char* kb[4];
; #pragma unroll
;     for (int dd = 0; dd < 4; ++dd) kb[dd] = K_lds + KB * SHM_K + KSWZ(r32, (dd * 16 + hi * 8) * 2);
; #pragma unroll
;     for (int d0 = 0; d0 < 8; ++d0) { const char* a = kb[d0 & 3] + (d0 >> 2) * 128;
;         bf16x8 b0 = *reinterpret_cast<const bf16x8*>(a);
;         bf16x8 b1 = *reinterpret_cast<const bf16x8*>(a + 32 * 256);
;         p0 = __builtin_amdgcn_mfma_f32_32x32x16_bf16(b0, qr[d0], p0, 0, 0, 0);
;         p1 = __builtin_amdgcn_mfma_f32_32x32x16_bf16(b1, qr[d0], p1, 0, 0, 0); }
; }
; template <int VB>
; __device__ __forceinline__ void pv_tile(f32x16* o, int vb0, bf16x8 pa0, bf16x8 pa1, bf16x8 pa2, bf16x8 pa3) {
;     ...
;     PV_D0(0); PV_D0(1); PV_D0(2); PV_D0(3);
	v_mfma_f32_32x32x16_bf16 v[64:79], v[100:103], v[128:131], v[64:79]
	v_add_f32_e32 v96, v116, v96
	v_add_f32_e32 v96, v117, v96
	v_add_f32_e32 v96, v118, v96
	v_add_f32_e32 v96, v119, v96
	v_add_f32_e32 v96, v114, v96
	v_add_f32_e32 v194, v115, v96
	v_mov_b32_e32 v234, v194
	v_cvt_pk_bf16_f32 v96, v169, v170
	v_cvt_pk_bf16_f32 v97, v171, v173
	v_cvt_pk_bf16_f32 v98, v174, v177
	v_cvt_pk_bf16_f32 v99, v172, v175
	v_permlane32_swap_b32_e32 v194, v234
	v_permlane32_swap_b32_e32 v96, v98
	v_permlane32_swap_b32_e32 v97, v99
	v_cvt_pk_bf16_f32 v100, v161, v163
	v_cvt_pk_bf16_f32 v101, v164, v167
	v_cvt_pk_bf16_f32 v102, v162, v165
	v_cvt_pk_bf16_f32 v103, v166, v168
	v_cvt_pk_bf16_f32 v104, v104, v105
	v_cvt_pk_bf16_f32 v105, v106, v107
	v_cvt_pk_bf16_f32 v106, v108, v109
	v_cvt_pk_bf16_f32 v107, v110, v111
	v_cvt_pk_bf16_f32 v108, v112, v113
	v_cvt_pk_bf16_f32 v109, v116, v117
	v_cvt_pk_bf16_f32 v110, v118, v119
	v_cvt_pk_bf16_f32 v111, v114, v115
	v_permlane32_swap_b32_e32 v100, v102
	v_permlane32_swap_b32_e32 v101, v103
	v_permlane32_swap_b32_e32 v104, v106
	v_permlane32_swap_b32_e32 v105, v107
	v_permlane32_swap_b32_e32 v108, v110
	v_permlane32_swap_b32_e32 v109, v111
	v_add_u32_e32 v212, s50, v202
	v_ashrrev_i32_e32 v213, 31, v212
	v_add_u32_e32 v116, 32, v212
	v_lshlrev_b64 v[112:113], 8, v[212:213]
	v_ashrrev_i32_e32 v117, 31, v116
	v_lshl_add_u64 v[114:115], v[208:209], 0, v[112:113]
	v_lshlrev_b64 v[116:117], 8, v[116:117]
	v_lshl_add_u64 v[112:113], v[210:211], 0, v[112:113]
	v_lshl_add_u64 v[118:119], v[208:209], 0, v[116:117]
	global_load_dwordx4 v[160:163], v[114:115], off
	global_load_dwordx4 v[164:167], v[118:119], off
	v_lshl_add_u64 v[114:115], v[210:211], 0, v[116:117]
	global_load_dwordx4 v[168:171], v[112:113], off
	global_load_dwordx4 v[172:175], v[114:115], off
	s_waitcnt lgkmcnt(0)
	s_nop 0
	v_mfma_f32_32x32x16_bf16 v[0:15], v[96:99], v[238:241], v[0:15]
	ds_read_b64_tr_b16 v[112:113], v225 offset:0x200
	ds_read_b64_tr_b16 v[114:115], v225 offset:0xa00
	v_mfma_f32_32x32x16_bf16 v[0:15], v[100:103], v[242:245], v[0:15]
	ds_read_b64_tr_b16 v[116:117], v225 offset:0x1200
	ds_read_b64_tr_b16 v[118:119], v225 offset:0x1a00
	v_mfma_f32_32x32x16_bf16 v[0:15], v[104:107], v[246:249], v[0:15]
	ds_read_b64_tr_b16 v[120:121], v225 offset:0x2200
	ds_read_b64_tr_b16 v[122:123], v225 offset:0x2a00
	v_mfma_f32_32x32x16_bf16 v[0:15], v[108:111], v[250:253], v[0:15]
	ds_read_b64_tr_b16 v[124:125], v225 offset:0x3200
	ds_read_b64_tr_b16 v[126:127], v225 offset:0x3a00
	s_waitcnt lgkmcnt(0)
	v_mfma_f32_32x32x16_bf16 v[48:63], v[96:99], v[112:115], v[48:63]
	ds_read_b64_tr_b16 v[112:113], v225 offset:0x400
	ds_read_b64_tr_b16 v[114:115], v225 offset:0xc00
	v_mfma_f32_32x32x16_bf16 v[48:63], v[100:103], v[116:119], v[48:63]
	ds_read_b64_tr_b16 v[116:117], v225 offset:0x1400
	ds_read_b64_tr_b16 v[118:119], v225 offset:0x1c00
	v_mfma_f32_32x32x16_bf16 v[48:63], v[104:107], v[120:123], v[48:63]
	ds_read_b64_tr_b16 v[120:121], v225 offset:0x2400
	ds_read_b64_tr_b16 v[122:123], v225 offset:0x2c00
	v_mfma_f32_32x32x16_bf16 v[48:63], v[108:111], v[124:127], v[48:63]
	ds_read_b64_tr_b16 v[124:125], v225 offset:0x3400
	ds_read_b64_tr_b16 v[126:127], v225 offset:0x3c00
	s_waitcnt lgkmcnt(0)
	v_mfma_f32_32x32x16_bf16 v[32:47], v[96:99], v[112:115], v[32:47]
	ds_read_b64_tr_b16 v[112:113], v225 offset:0x600
	ds_read_b64_tr_b16 v[114:115], v225 offset:0xe00
	v_mfma_f32_32x32x16_bf16 v[32:47], v[100:103], v[116:119], v[32:47]
	ds_read_b64_tr_b16 v[116:117], v225 offset:0x1600
	ds_read_b64_tr_b16 v[118:119], v225 offset:0x1e00
	v_mfma_f32_32x32x16_bf16 v[32:47], v[104:107], v[120:123], v[32:47]
	ds_read_b64_tr_b16 v[120:121], v225 offset:0x2600
	ds_read_b64_tr_b16 v[122:123], v225 offset:0x2e00
	v_mfma_f32_32x32x16_bf16 v[32:47], v[108:111], v[124:127], v[32:47]
	ds_read_b64_tr_b16 v[124:125], v225 offset:0x3600
	ds_read_b64_tr_b16 v[126:127], v225 offset:0x3e00
	s_waitcnt lgkmcnt(0)
	s_sub_i32 s40, s50, 64
	s_cmp_gt_i32 s40, s49
	s_cbranch_scc0 .Lmy_nomask1
	v_mov_b32_e32 v64, v220
	v_mov_b32_e32 v65, v220
	v_mov_b32_e32 v66, v220
	v_mov_b32_e32 v67, v220
	v_mov_b32_e32 v68, v220
	v_mov_b32_e32 v69, v220
	v_mov_b32_e32 v70, v220
	v_mov_b32_e32 v71, v220
	v_mov_b32_e32 v72, v220
	v_mov_b32_e32 v73, v220
	v_mov_b32_e32 v74, v220
	v_mov_b32_e32 v75, v220
	v_mov_b32_e32 v76, v220
	v_mov_b32_e32 v77, v220
	v_mov_b32_e32 v78, v220
	v_mov_b32_e32 v79, v220
	v_mov_b32_e32 v80, v220
	v_mov_b32_e32 v81, v220
	v_mov_b32_e32 v82, v220
	v_mov_b32_e32 v83, v220
	v_mov_b32_e32 v84, v220
	v_mov_b32_e32 v85, v220
	v_mov_b32_e32 v86, v220
	v_mov_b32_e32 v87, v220
	v_mov_b32_e32 v88, v220
	v_mov_b32_e32 v89, v220
	v_mov_b32_e32 v90, v220
	v_mov_b32_e32 v91, v220
	v_mov_b32_e32 v92, v220
	v_mov_b32_e32 v93, v220
	v_mov_b32_e32 v94, v220
	v_mov_b32_e32 v95, v220

; __device__ __forceinline__ void partialSM(f32x16& p0, f32x16& p1, float& m_reg, float& mn, float& alpha) {
;     float pmax = p0[0]; for (int r = 1; r < 16; ++r) pmax = fmaxf(pmax, p0[r]); for (int r = 0; r < 16; ++r) pmax = fmaxf(pmax, p1[r]);
;     { auto rr = __builtin_amdgcn_permlane32_swap(__float_as_uint(pmax), __float_as_uint(pmax), false, false);
;       pmax = fmaxf(__uint_as_float(rr[0]), __uint_as_float(rr[1])); }
;     constexpr float C2 = 1.4426950408889634f * SCALE;
;     if (__builtin_expect(__all((pmax - m_reg) * SCALE <= THR), 1)) { mn = m_reg; alpha = 1.f; }
;     else { mn = fmaxf(m_reg, pmax); alpha = __builtin_amdgcn_exp2f((m_reg - mn) * C2); m_reg = mn; }
;     const float mnL = -mn * C2;
;     for (int r = 0; r < 16; ++r) p0[r] = fmaf(p0[r], C2, mnL); for (int r = 0; r < 16; ++r) p1[r] = fmaf(p1[r], C2, mnL);
;     for (int r = 0; r < 16; ++r) p0[r] = __builtin_amdgcn_exp2f(p0[r]);
; }
; __device__ __forceinline__ void finishSM(f32x16& p0, f32x16& p1, float alpha, float& l_reg, bf16x8& pa0, bf16x8& pa1, bf16x8& pa2, bf16x8& pa3) {
;     for (int r = 0; r < 16; ++r) p1[r] = __builtin_amdgcn_exp2f(p1[r]);
;     float ps = 0; for (int r = 0; r < 16; ++r) ps += p0[r]; for (int r = 0; r < 16; ++r) ps += p1[r];
;     { auto rr = __builtin_amdgcn_permlane32_swap(__float_as_uint(ps), __float_as_uint(ps), false, false);
;       ps = __uint_as_float(rr[0]) + __uint_as_float(rr[1]); }
;     l_reg = l_reg * alpha + ps;
;     ...
;     PK4(p0, 0, pa0); PK4(p0, 8, pa1); PK4(p1, 0, pa2); PK4(p1, 8, pa3);
;     ...
; }
; template <int KB>
; __device__ __forceinline__ void qkt(f32x16& p0, f32x16& p1, const char* K_lds, int r32, int hi, const bf16x8* qr) {
;     p0 = f32x16{}; p1 = f32x16{};
;     const char* kb[4];
; #pragma unroll
;     for (int dd = 0; dd < 4; ++dd) kb[dd] = K_lds + KB * SHM_K + KSWZ(r32, (dd * 16 + hi * 8) * 2);
; #pragma unroll
;     for (int d0 = 0; d0 < 8; ++d0) { const char* a = kb[d0 & 3] + (d0 >> 2) * 128;
;         bf16x8 b0 = *reinterpret_cast<const bf16x8*>(a);
;         bf16x8 b1 = *reinterpret_cast<const bf16x8*>(a + 32 * 256);
;         p0 = __builtin_amdgcn_mfma_f32_32x32x16_bf16(b0, qr[d0], p0, 0, 0, 0);
;         p1 = __builtin_amdgcn_mfma_f32_32x32x16_bf16(b1, qr[d0], p1, 0, 0, 0); }
; }
.LBB0_324:
	v_cndmask_b32_e64 v235, v77, v176, s[40:41]
	v_mul_f32_e32 v176, 0xbe0293ee, v235
	v_fmamk_f32 v77, v98, 0x3e0293ee, v176
	v_fmamk_f32 v78, v97, 0x3e0293ee, v176
	v_fmamk_f32 v79, v96, 0x3e0293ee, v176
	v_fmamk_f32 v96, v83, 0x3e0293ee, v176
	v_fmamk_f32 v97, v84, 0x3e0293ee, v176
	v_fmamk_f32 v98, v85, 0x3e0293ee, v176
	v_fmamk_f32 v99, v86, 0x3e0293ee, v176
	v_fmamk_f32 v100, v87, 0x3e0293ee, v176
	v_fmamk_f32 v101, v88, 0x3e0293ee, v176
	v_fmamk_f32 v102, v89, 0x3e0293ee, v176
	v_fmamk_f32 v103, v90, 0x3e0293ee, v176
	v_fmamk_f32 v104, v91, 0x3e0293ee, v176
	v_fmamk_f32 v105, v92, 0x3e0293ee, v176
	v_fmamk_f32 v106, v93, 0x3e0293ee, v176
	v_fmamk_f32 v107, v94, 0x3e0293ee, v176
	v_fmamk_f32 v108, v95, 0x3e0293ee, v176
	v_fmamk_f32 v83, v64, 0x3e0293ee, v176
	v_fmamk_f32 v84, v65, 0x3e0293ee, v176
	v_fmamk_f32 v93, v66, 0x3e0293ee, v176
	v_fmamk_f32 v94, v67, 0x3e0293ee, v176
	v_fmamk_f32 v95, v68, 0x3e0293ee, v176
	v_fmamk_f32 v85, v69, 0x3e0293ee, v176
	v_fmamk_f32 v86, v70, 0x3e0293ee, v176
	v_fmamk_f32 v87, v71, 0x3e0293ee, v176
	v_fmamk_f32 v88, v72, 0x3e0293ee, v176
	v_fmamk_f32 v89, v73, 0x3e0293ee, v176
	v_fmamk_f32 v90, v74, 0x3e0293ee, v176
	v_fmamk_f32 v91, v75, 0x3e0293ee, v176
	v_fmamk_f32 v92, v76, 0x3e0293ee, v176
	v_exp_f32_e32 v64, v77
	v_exp_f32_e32 v65, v78
	v_exp_f32_e32 v66, v79
	v_exp_f32_e32 v67, v96
	v_exp_f32_e32 v68, v97
	v_exp_f32_e32 v69, v98
	v_exp_f32_e32 v70, v99
	v_exp_f32_e32 v71, v100
	v_exp_f32_e32 v72, v101
	v_exp_f32_e32 v73, v102
	v_exp_f32_e32 v74, v103
	v_exp_f32_e32 v75, v104
	v_exp_f32_e32 v76, v105
	v_exp_f32_e32 v77, v106
	v_exp_f32_e32 v78, v107
	v_exp_f32_e32 v79, v108
	v_fmamk_f32 v177, v82, 0x3e0293ee, v176
	v_fmamk_f32 v178, v81, 0x3e0293ee, v176
	v_fmac_f32_e32 v176, 0x3e0293ee, v80
	s_waitcnt lgkmcnt(0)
	s_barrier
	ds_read_b128 v[96:99], v201 offset:32768
	ds_read_b128 v[100:103], v201 offset:40960
	ds_read_b128 v[180:183], v230 offset:32768
	ds_read_b128 v[184:187], v230 offset:40960
	v_exp_f32_e32 v81, v84
	v_exp_f32_e32 v84, v95
	s_waitcnt lgkmcnt(3)
	v_mfma_f32_32x32x16_bf16 v[112:127], v[96:99], v[156:159], 0
	v_exp_f32_e32 v95, v176
	v_add_f32_e32 v176, 0, v64
	v_add_f32_e32 v176, v65, v176
	v_add_f32_e32 v176, v66, v176
	v_add_f32_e32 v176, v67, v176
	v_add_f32_e32 v176, v68, v176
	v_add_f32_e32 v176, v69, v176
	s_waitcnt lgkmcnt(2)
	v_mfma_f32_32x32x16_bf16 v[96:111], v[100:103], v[156:159], 0
	v_add_f32_e32 v176, v70, v176
	v_add_f32_e32 v176, v71, v176
	v_add_f32_e32 v176, v72, v176
	v_add_f32_e32 v176, v73, v176
	v_add_f32_e32 v176, v74, v176
	v_add_f32_e32 v176, v75, v176
	v_exp_f32_e32 v80, v83
	s_waitcnt lgkmcnt(1)
	v_mfma_f32_32x32x16_bf16 v[112:127], v[180:183], v[152:155], v[112:127]
	v_add_f32_e32 v176, v76, v176
	v_add_f32_e32 v176, v77, v176
	v_exp_f32_e32 v82, v93
	v_add_f32_e32 v176, v78, v176
	v_exp_f32_e32 v83, v94
	v_add_f32_e32 v176, v79, v176
	v_add_f32_e32 v176, v80, v176
	s_waitcnt lgkmcnt(0)
	v_mfma_f32_32x32x16_bf16 v[96:111], v[184:187], v[152:155], v[96:111]
	ds_read_b128 v[180:183], v229 offset:32768
	ds_read_b128 v[184:187], v229 offset:40960
	v_exp_f32_e32 v85, v85
	v_add_f32_e32 v176, v81, v176
	v_exp_f32_e32 v86, v86
	v_add_f32_e32 v176, v82, v176
	v_exp_f32_e32 v87, v87
	v_add_f32_e32 v176, v83, v176
	s_waitcnt lgkmcnt(1)
	v_mfma_f32_32x32x16_bf16 v[112:127], v[180:183], v[148:151], v[112:127]
	v_exp_f32_e32 v88, v88
	v_add_f32_e32 v176, v84, v176
	v_exp_f32_e32 v89, v89
	v_add_f32_e32 v176, v85, v176
	v_exp_f32_e32 v90, v90
	v_add_f32_e32 v176, v86, v176
	v_exp_f32_e32 v91, v91
	s_waitcnt lgkmcnt(0)
	v_mfma_f32_32x32x16_bf16 v[96:111], v[184:187], v[148:151], v[96:111]
	ds_read_b128 v[180:183], v207 offset:32768
	ds_read_b128 v[184:187], v207 offset:40960
	v_add_f32_e32 v176, v87, v176
	v_exp_f32_e32 v92, v92
	v_add_f32_e32 v176, v88, v176
	v_exp_f32_e32 v93, v177
	v_add_f32_e32 v176, v89, v176
	v_exp_f32_e32 v94, v178
	s_waitcnt lgkmcnt(1)
	v_mfma_f32_32x32x16_bf16 v[112:127], v[180:183], v[144:147], v[112:127]
	v_add_f32_e32 v176, v90, v176
	v_add_f32_e32 v176, v91, v176
	v_add_f32_e32 v176, v92, v176
	v_add_f32_e32 v176, v93, v176
	v_add_f32_e32 v176, v94, v176
	v_add_f32_e32 v236, v95, v176
	v_mov_b32_e32 v237, v236
	s_waitcnt lgkmcnt(0)
	v_mfma_f32_32x32x16_bf16 v[96:111], v[184:187], v[144:147], v[96:111]
	ds_read_b128 v[180:183], v201 offset:32896
	ds_read_b128 v[184:187], v201 offset:41088
	v_cvt_pk_bf16_f32 v176, v64, v65
	v_cvt_pk_bf16_f32 v177, v66, v67
	v_cvt_pk_bf16_f32 v178, v68, v69
	v_cvt_pk_bf16_f32 v179, v70, v71
	v_cvt_pk_bf16_f32 v188, v88, v89
	v_cvt_pk_bf16_f32 v189, v90, v91
	s_waitcnt lgkmcnt(1)
	v_mfma_f32_32x32x16_bf16 v[112:127], v[180:183], v[140:143], v[112:127]
	v_cvt_pk_bf16_f32 v190, v92, v93
	v_cvt_pk_bf16_f32 v191, v94, v95
	v_permlane32_swap_b32_e32 v236, v237
	v_permlane32_swap_b32_e32 v176, v178
	v_permlane32_swap_b32_e32 v177, v179
	s_waitcnt lgkmcnt(0)
	v_mfma_f32_32x32x16_bf16 v[96:111], v[184:187], v[140:143], v[96:111]
	ds_read_b128 v[180:183], v230 offset:32896
	ds_read_b128 v[184:187], v230 offset:41088
	v_permlane32_swap_b32_e32 v188, v190
	v_permlane32_swap_b32_e32 v189, v191
	s_waitcnt lgkmcnt(1)
	v_mfma_f32_32x32x16_bf16 v[112:127], v[180:183], v[136:139], v[112:127]
	s_waitcnt lgkmcnt(0)
	v_mfma_f32_32x32x16_bf16 v[96:111], v[184:187], v[136:139], v[96:111]
	ds_read_b128 v[180:183], v229 offset:32896
	ds_read_b128 v[184:187], v229 offset:41088
	s_waitcnt lgkmcnt(1)
	v_mfma_f32_32x32x16_bf16 v[112:127], v[180:183], v[132:135], v[112:127]
	s_waitcnt lgkmcnt(0)
	v_mfma_f32_32x32x16_bf16 v[96:111], v[184:187], v[132:135], v[96:111]
	ds_read_b128 v[180:183], v207 offset:32896
	ds_read_b128 v[184:187], v207 offset:41088
	ds_read_b64_tr_b16 v[238:239], v225 offset:0x4000
	ds_read_b64_tr_b16 v[240:241], v225 offset:0x4800
	ds_read_b64_tr_b16 v[242:243], v225 offset:0x5000
	ds_read_b64_tr_b16 v[244:245], v225 offset:0x5800
	ds_read_b64_tr_b16 v[246:247], v225 offset:0x6000
	ds_read_b64_tr_b16 v[248:249], v225 offset:0x6800
	ds_read_b64_tr_b16 v[250:251], v225 offset:0x7000
	ds_read_b64_tr_b16 v[252:253], v225 offset:0x7800
	s_waitcnt lgkmcnt(9)
	v_mfma_f32_32x32x16_bf16 v[112:127], v[180:183], v[128:131], v[112:127]
	v_cvt_pk_bf16_f32 v180, v72, v73
	v_cvt_pk_bf16_f32 v181, v74, v75
	v_cvt_pk_bf16_f32 v182, v76, v77
	v_cvt_pk_bf16_f32 v183, v78, v79
	s_nop 0
	v_permlane32_swap_b32_e32 v180, v182
	v_permlane32_swap_b32_e32 v181, v183
	s_waitcnt lgkmcnt(8)
	v_mfma_f32_32x32x16_bf16 v[96:111], v[184:187], v[128:131], v[96:111]
	v_cvt_pk_bf16_f32 v184, v80, v81
	v_cvt_pk_bf16_f32 v185, v82, v83
	v_cvt_pk_bf16_f32 v186, v84, v85
	v_cvt_pk_bf16_f32 v187, v86, v87
	s_nop 0
	v_permlane32_swap_b32_e32 v184, v186
	v_permlane32_swap_b32_e32 v185, v187
	s_add_i32 s40, s80, 1
	s_cmp_lt_u32 s40, s79
	s_cselect_b64 s[42:43], -1, 0
	s_cmp_ge_u32 s40, s79
	s_cbranch_scc1 .LBB0_326
; template <int VB>
; __device__ __forceinline__ void pv_tile(f32x16* o, int vb0, bf16x8 pa0, bf16x8 pa1, bf16x8 pa2, bf16x8 pa3) {
;     ...
;     PV_D0(0); PV_D0(1); PV_D0(2); PV_D0(3);
;     ...
; }
	v_add_u32_e32 v160, 64, v212
	v_add_u32_e32 v162, 0x60, v212
	v_ashrrev_i32_e32 v161, 31, v160
	v_ashrrev_i32_e32 v163, 31, v162
	v_lshlrev_b64 v[168:169], 8, v[160:161]
	v_lshlrev_b64 v[170:171], 8, v[162:163]
	v_lshl_add_u64 v[160:161], v[208:209], 0, v[168:169]
	v_lshl_add_u64 v[164:165], v[208:209], 0, v[170:171]
	v_lshl_add_u64 v[168:169], v[210:211], 0, v[168:169]
	v_lshl_add_u64 v[172:173], v[210:211], 0, v[170:171]
	global_load_dwordx4 v[160:163], v[160:161], off
	s_nop 0
	global_load_dwordx4 v[164:167], v[164:165], off
	s_nop 0
	global_load_dwordx4 v[168:171], v[168:169], off
	s_nop 0
	global_load_dwordx4 v[172:175], v[172:173], off
.LBB0_326:
	s_waitcnt lgkmcnt(0)
	s_nop 0
	v_mfma_f32_32x32x16_bf16 v[0:15], v[176:179], v[238:241], v[0:15]
	ds_read_b64_tr_b16 v[238:239], v225 offset:0x4200
	ds_read_b64_tr_b16 v[240:241], v225 offset:0x4a00
	v_mfma_f32_32x32x16_bf16 v[0:15], v[180:183], v[242:245], v[0:15]
	ds_read_b64_tr_b16 v[242:243], v225 offset:0x5200
	ds_read_b64_tr_b16 v[244:245], v225 offset:0x5a00
	v_mfma_f32_32x32x16_bf16 v[0:15], v[184:187], v[246:249], v[0:15]
	ds_read_b64_tr_b16 v[246:247], v225 offset:0x6200
	ds_read_b64_tr_b16 v[248:249], v225 offset:0x6a00
	v_mfma_f32_32x32x16_bf16 v[0:15], v[188:191], v[250:253], v[0:15]
	ds_read_b64_tr_b16 v[250:251], v225 offset:0x7200
	ds_read_b64_tr_b16 v[252:253], v225 offset:0x7a00
	s_waitcnt lgkmcnt(0)
	v_mfma_f32_32x32x16_bf16 v[48:63], v[176:179], v[238:241], v[48:63]
	ds_read_b64_tr_b16 v[238:239], v225 offset:0x4400
	ds_read_b64_tr_b16 v[240:241], v225 offset:0x4c00
	v_mfma_f32_32x32x16_bf16 v[48:63], v[180:183], v[242:245], v[48:63]
	ds_read_b64_tr_b16 v[242:243], v225 offset:0x5400
	ds_read_b64_tr_b16 v[244:245], v225 offset:0x5c00
	v_mfma_f32_32x32x16_bf16 v[48:63], v[184:187], v[246:249], v[48:63]
	ds_read_b64_tr_b16 v[246:247], v225 offset:0x6400
	ds_read_b64_tr_b16 v[248:249], v225 offset:0x6c00
	v_mfma_f32_32x32x16_bf16 v[48:63], v[188:191], v[250:253], v[48:63]
	ds_read_b64_tr_b16 v[250:251], v225 offset:0x7400
	ds_read_b64_tr_b16 v[252:253], v225 offset:0x7c00
	s_waitcnt lgkmcnt(0)
	v_mfma_f32_32x32x16_bf16 v[32:47], v[176:179], v[238:241], v[32:47]
	ds_read_b64_tr_b16 v[238:239], v225 offset:0x4600
	ds_read_b64_tr_b16 v[240:241], v225 offset:0x4e00
	v_mfma_f32_32x32x16_bf16 v[32:47], v[180:183], v[242:245], v[32:47]
	ds_read_b64_tr_b16 v[242:243], v225 offset:0x5600
	ds_read_b64_tr_b16 v[244:245], v225 offset:0x5e00
	v_mfma_f32_32x32x16_bf16 v[32:47], v[184:187], v[246:249], v[32:47]
	ds_read_b64_tr_b16 v[246:247], v225 offset:0x6600
	ds_read_b64_tr_b16 v[248:249], v225 offset:0x6e00
	v_mfma_f32_32x32x16_bf16 v[32:47], v[188:191], v[250:253], v[32:47]
	ds_read_b64_tr_b16 v[250:251], v225 offset:0x7600
	ds_read_b64_tr_b16 v[252:253], v225 offset:0x7e00
	s_waitcnt lgkmcnt(0)
	v_mfma_f32_32x32x16_bf16 v[16:31], v[176:179], v[238:241], v[16:31]
	s_cmp_gt_i32 s50, s49
	s_cbranch_scc0 .Lmy_nomask2
	v_mov_b32_e32 v96, v220
	v_mov_b32_e32 v97, v220
	v_mov_b32_e32 v98, v220
	v_mov_b32_e32 v99, v220
	v_mov_b32_e32 v100, v220
	v_mov_b32_e32 v101, v220
	v_mov_b32_e32 v102, v220
	v_mov_b32_e32 v103, v220
	v_mov_b32_e32 v104, v220
	v_mov_b32_e32 v105, v220
	v_mov_b32_e32 v106, v220
	v_mov_b32_e32 v107, v220
	v_mov_b32_e32 v108, v220
	v_mov_b32_e32 v109, v220
	v_mov_b32_e32 v110, v220
	v_mov_b32_e32 v111, v220
	v_mov_b32_e32 v112, v220
	v_mov_b32_e32 v113, v220
	v_mov_b32_e32 v114, v220
	v_mov_b32_e32 v115, v220
	v_mov_b32_e32 v116, v220
	v_mov_b32_e32 v117, v220
	v_mov_b32_e32 v118, v220
	v_mov_b32_e32 v119, v220
	v_mov_b32_e32 v120, v220
	v_mov_b32_e32 v121, v220
	v_mov_b32_e32 v122, v220
	v_mov_b32_e32 v123, v220
	v_mov_b32_e32 v124, v220
	v_mov_b32_e32 v125, v220
	v_mov_b32_e32 v126, v220
	v_mov_b32_e32 v127, v220

; #define PG8_STAGE(bufoff, gbase, voff) do { _Pragma("unroll") for (int _i = 0; _i < 2; ++_i) \
;         __builtin_amdgcn_global_load_lds((const unsigned*)((const char*)(gbase) + (voff)[_i]), (PG8_LAS unsigned*)(lds + (bufoff) + ldsw + _i * 8192), 16, 0, 0); } while (0)
; #define PG8_BAR __builtin_amdgcn_s_barrier()
; template <class Epi, class Sched, bool ALIGN_EPI = false, bool SP2 = false>
; __device__ __forceinline__ void gemm_phase(PG8_LAS unsigned char* lds, const Gemm g, const Sched& S, const Epi& E) {
;     ...
;     const int tid = tid_, wid = __builtin_amdgcn_readfirstlane(tid >> 6), lane = tid & 63, wr = wid >> 2, wc = wid & 3, fr = lane & 15, fq = lane >> 4;
;     const int K = g.K, nt = K / BK;
;     unsigned voffA[2], voffB[2];
; #pragma unroll
;     for (int i = 0; i < 2; ++i) { int R, C; stage_rc(tid * 16 + i * 8192, R, C); const int Rb = Epi::PERM ? ((R & ~31) + perm32(R & 31)) : R;
;         voffA[i] = (unsigned)(R * K + C) * 2u; voffB[i] = (unsigned)(Rb * K + C) * 2u; }
;     const size_t kstep = (size_t)(BK * 2);
;     const size_t hstep = (size_t)HALF * K * 2;
;     const size_t tstep = 2 * hstep;
;     const unsigned ldsw = (unsigned)wid * 1024u;
;     const int aoff = lds_byte(wr * 64 + fr, fq * 8), boff = lds_byte(wc * 32 + fr, fq * 8);
;     ...
;     Unit cur, nxt; int ui = 0;
;     if (!S.next(0, cur)) return;
;     f32x4 acc[2][2][4][2];
; #pragma unroll
;     for (int a = 0; a < 2; ++a)
; #pragma unroll
;         for (int b = 0; b < 2; ++b)
; #pragma unroll
;             for (int m = 0; m < 4; ++m)
; #pragma unroll
;                 for (int n = 0; n < 2; ++n) acc[a][b][m][n] = (f32x4){0.f, 0.f, 0.f, 0.f};
;     bf16x8 At[4][2], B0[2][2], B1[2][2];
;     const char* cA = (const char*)g.A + (size_t)cur.pm * tstep; const char* cB = (const char*)g.Bt + (size_t)cur.pn * tstep;
;     S.a_ready(cur);
;     if constexpr (SP2) {
;         PG8_STAGE(PG8_SB(0, 0), cB, voffB); PG8_STAGE(PG8_SB(0, 1), cB + hstep, voffB); PG8_STAGE(PG8_SA(0, 0), cA, voffA); PG8_STAGE(PG8_SA(0, 1), cA + hstep, voffA);
;         if (wr == 1) PG8_BAR;
;         PG8_WAIT_V(2); PG8_BAR;
; __global__ void __launch_bounds__(NTHR, 2) mega_fwd(Args args) {
;     ...
;         pg8::StaticOrder S; S.init(T, DM, G, bx);
;         { pg8::Gemm g{YC, WC, T, DM, CW}; pg8::EpiMerge<false> E{MG, GT}; pg8::gemm_phase<pg8::EpiMerge<false>, pg8::StaticOrder, true, true>(L, g, S, E); }
.LBB0_540:
	s_or_b64 exec, exec, s[14:15]
	s_nop 0
	s_nop 0
	s_nop 0
	s_nop 0
	s_nop 0
	s_nop 0
	s_nop 0
	s_nop 0
	s_nop 0
	s_nop 0
	s_cmpk_lt_i32 s2, 0x400
	s_mov_b64 s[22:23], s[0:1]
	s_mov_b64 s[16:17], s[0:1]
	s_mov_b64 s[24:25], s[0:1]
	s_mov_b64 s[18:19], s[0:1]
	s_mov_b64 s[14:15], s[0:1]
	s_waitcnt lgkmcnt(0)
	s_barrier
	s_cselect_b64 s[48:49], -1, 0
	s_lshr_b32 s13, s33, 29
	s_add_i32 s13, s2, s13
	s_load_dwordx2 s[14:15], s[14:15], 0xc8
	s_ashr_i32 s56, s13, 3
	s_and_b32 s13, s13, -8
	s_load_dwordx2 s[20:21], s[16:17], 0xc8
	s_nop 0
	s_load_dwordx2 s[18:19], s[18:19], 0xc8
	s_mov_b64 s[16:17], s[0:1]
	s_sub_i32 s59, s2, s13
	s_cmp_lt_i32 s59, 0
	s_load_dwordx2 s[16:17], s[16:17], 0xc8
	s_cselect_b64 s[42:43], -1, 0
	s_lshl_b32 s57, s59, 7
	s_waitcnt lgkmcnt(0)
	s_add_u32 s14, s14, 0x2f800000
	s_addc_u32 s15, s15, 0
	s_waitcnt vmcnt(27)
	v_mov_b32_e32 v14, v216
	s_cmpk_gt_i32 s2, 0x3ff
	s_mul_i32 s58, s59, 0x81
	s_nop 0
	v_readfirstlane_b32 s28, v14
	s_cbranch_scc1 .LBB0_560
	v_lshlrev_b32_e32 v0, 4, v14
	v_add_u32_e32 v1, 0x2000, v0
	v_ashrrev_i32_e32 v2, 31, v1
	v_lshrrev_b32_e32 v2, 22, v2
	v_add_u32_e32 v2, v1, v2
	v_ashrrev_i32_e32 v8, 10, v2
	v_mul_i32_i24_e32 v2, 0x400, v8
	v_sub_u32_e32 v1, v1, v2
	v_lshrrev_b32_e32 v2, 4, v1
	v_bitop3_b32 v1, v2, v1, 32 bitop3:0x6c
	v_ashrrev_i32_e32 v2, 31, v1
	s_load_dwordx2 s[22:23], s[22:23], 0xc8
	s_nop 0
	s_load_dwordx2 s[24:25], s[24:25], 0xc8
	v_lshrrev_b32_e32 v2, 26, v2
	v_add_u32_e32 v2, v1, v2
	v_lshlrev_b32_e32 v3, 3, v8
	v_ashrrev_i32_e32 v9, 6, v2
	v_and_b32_e32 v3, -16, v3
	v_add_u32_e32 v3, v9, v3
	s_waitcnt lgkmcnt(0)
	s_add_u32 s13, s22, 0x3b800000
	v_and_b32_e32 v4, 3, v9
	s_mov_b32 s22, 0x1fffe0
	v_lshrrev_b32_e32 v5, 2, v3
	v_lshlrev_b32_e32 v6, 1, v3
	v_and_b32_e32 v2, 0xc0, v2
	v_and_or_b32 v4, v3, s22, v4
	v_and_b32_e32 v5, 4, v5
	v_and_b32_e32 v6, 24, v6
	v_sub_u32_e32 v1, v1, v2
	v_mov_b32_e32 v2, 1
	v_or3_b32 v4, v4, v5, v6
	v_lshlrev_b32_e32 v5, 5, v8
	v_ashrrev_i16_sdwa v1, v2, sext(v1) dst_sel:DWORD dst_unused:UNUSED_PAD src0_sel:DWORD src1_sel:BYTE_0
	v_and_b32_e32 v5, 32, v5
	v_bfe_i32 v10, v1, 0, 16
	v_add_lshl_u32 v1, v5, v10, 1
	s_waitcnt vmcnt(6)
	v_lshl_add_u32 v152, v4, 11, v1
	v_lshl_add_u32 v154, v3, 11, v1
	v_bfe_i32 v1, v14, 27, 1
	v_lshrrev_b32_e32 v1, 22, v1
	v_add_u32_e32 v1, v0, v1
	v_and_b32_e32 v1, 0xfffffc00, v1
	v_sub_u32_e32 v0, v0, v1
	v_lshrrev_b32_e32 v1, 4, v0
	v_ashrrev_i32_e32 v3, 31, v14
	v_bitop3_b32 v0, v1, v0, 32 bitop3:0x6c
	v_lshrrev_b32_e32 v3, 26, v3
	v_ashrrev_i32_e32 v1, 31, v0
	v_add_u32_e32 v3, v14, v3
	s_addc_u32 s47, s23, 0
	v_lshrrev_b32_e32 v1, 26, v1
	v_ashrrev_i32_e32 v12, 6, v3
	s_add_u32 s60, s24, 0x2600000
	v_add_u32_e32 v1, v0, v1
	v_lshlrev_b32_e32 v3, 3, v12
	s_addc_u32 s61, s25, 0
	s_ashr_i32 s26, s28, 6
	v_ashrrev_i32_e32 v11, 6, v1
	v_and_b32_e32 v3, -16, v3
	s_ashr_i32 s27, s28, 8
	s_lshl_b32 s62, s26, 10
	v_add_u32_e32 v3, v11, v3
	v_and_b32_e32 v4, 3, v11
	v_and_or_b32 v4, v3, s22, v4
	s_and_b64 s[22:23], s[42:43], exec
	s_cselect_b32 s22, s58, s57
	s_add_i32 s22, s22, s56
	s_ashr_i32 s23, s22, 31
	s_lshr_b32 s23, s23, 27
	s_add_i32 s23, s22, s23
	s_ashr_i32 s24, s23, 5
	s_and_b32 s23, s23, 0xffe0
	s_sub_i32 s22, s22, s23
	s_bfe_i32 s23, s22, 0x80000
	s_bfe_u32 s23, s23, 0x2000d
	s_add_i32 s23, s22, s23
	s_lshl_b32 s25, s24, 2
	s_bfe_i32 s24, s23, 0x80000
	s_and_b32 s23, s23, 0xfc
	s_sub_i32 s22, s22, s23
	s_sext_i32_i16 s24, s24
	s_sext_i32_i8 s22, s22
	v_lshrrev_b32_e32 v5, 2, v3
	v_lshlrev_b32_e32 v6, 1, v3
	v_and_b32_e32 v1, 0xc0, v1
	s_lshr_b32 s24, s24, 2
	s_add_i32 s44, s25, s22
	v_and_b32_e32 v5, 4, v5
	v_and_b32_e32 v6, 24, v6
	v_sub_u32_e32 v0, v0, v1
	s_ashr_i32 s45, s44, 31
	s_bfe_i64 s[30:31], s[24:25], 0x100000
	v_or3_b32 v4, v4, v5, v6
	v_lshlrev_b32_e32 v5, 5, v12
	v_ashrrev_i16_sdwa v0, v2, sext(v0) dst_sel:DWORD dst_unused:UNUSED_PAD src0_sel:DWORD src1_sel:BYTE_0
	s_lshl_b64 s[22:23], s[44:45], 19
	s_lshl_b64 s[30:31], s[30:31], 19
	v_and_b32_e32 v5, 32, v5
	v_bfe_i32 v13, v0, 0, 16
	s_add_u32 s52, s60, s30
	v_add_lshl_u32 v0, v5, v13, 1
	s_addc_u32 s53, s61, s31
	s_add_i32 s63, s62, 0
	v_lshl_add_u32 v156, v4, 11, v0
	s_add_i32 m0, s63, 0x10000
	v_lshl_add_u32 v158, v3, 11, v0
	global_load_lds_dwordx4 v156, s[52:53]
	s_add_i32 m0, s63, 0x12000
	s_add_u32 s30, s52, 0x40000
	global_load_lds_dwordx4 v152, s[52:53]
	s_addc_u32 s31, s53, 0
	s_add_i32 m0, s63, 0x14000
	v_mov_b32_e32 v157, 0
	global_load_lds_dwordx4 v156, s[30:31]
	s_add_i32 m0, s63, 0x16000
	s_add_u32 s50, s13, s22
	s_addc_u32 s51, s47, s23
	s_add_i32 s64, s63, 0x2000
	global_load_lds_dwordx4 v152, s[30:31]
	s_mov_b32 m0, s63
	s_add_u32 s22, s50, 0x40000
	global_load_lds_dwordx4 v158, s[50:51]
	s_mov_b32 m0, s64
	s_addc_u32 s23, s51, 0
	s_add_i32 s65, s63, 0x4000
	global_load_lds_dwordx4 v154, s[50:51]
	s_mov_b32 m0, s65
	s_add_i32 s66, s63, 0x6000
	global_load_lds_dwordx4 v158, s[22:23]
	s_mov_b32 m0, s66
	v_mov_b32_e32 v153, v157
	global_load_lds_dwordx4 v154, s[22:23]
	v_mov_b32_e32 v159, v157
	v_mov_b32_e32 v155, v157
	s_cmp_eq_u32 s27, 1
	v_lshl_add_u64 v[6:7], s[52:53], 0, v[156:157]
	v_lshl_add_u64 v[4:5], s[52:53], 0, v[152:153]
	v_lshl_add_u64 v[0:1], s[50:51], 0, v[158:159]
	s_cselect_b64 s[22:23], -1, 0
	s_cmp_lg_u32 s27, 1
	v_lshl_add_u64 v[2:3], s[50:51], 0, v[154:155]
	s_cbranch_scc1 .LBB0_543
	s_barrier

; #define PG8_STAGE(bufoff, gbase, voff) do { _Pragma("unroll") for (int _i = 0; _i < 2; ++_i) \
;         __builtin_amdgcn_global_load_lds((const unsigned*)((const char*)(gbase) + (voff)[_i]), (PG8_LAS unsigned*)(lds + (bufoff) + ldsw + _i * 8192), 16, 0, 0); } while (0)
; #define PG8_BAR __builtin_amdgcn_s_barrier()
; template <class Epi, class Sched, bool ALIGN_EPI = false, bool SP2 = false>
; __device__ __forceinline__ void gemm_phase(PG8_LAS unsigned char* lds, const Gemm g, const Sched& S, const Epi& E) {
;     ...
;     const int tid = tid_, wid = __builtin_amdgcn_readfirstlane(tid >> 6), lane = tid & 63, wr = wid >> 2, wc = wid & 3, fr = lane & 15, fq = lane >> 4;
;     const int K = g.K, nt = K / BK;
;     unsigned voffA[2], voffB[2];
; #pragma unroll
;     for (int i = 0; i < 2; ++i) { int R, C; stage_rc(tid * 16 + i * 8192, R, C); const int Rb = Epi::PERM ? ((R & ~31) + perm32(R & 31)) : R;
;         voffA[i] = (unsigned)(R * K + C) * 2u; voffB[i] = (unsigned)(Rb * K + C) * 2u; }
;     const size_t kstep = (size_t)(BK * 2);
;     const size_t hstep = (size_t)HALF * K * 2;
;     const size_t tstep = 2 * hstep;
;     const unsigned ldsw = (unsigned)wid * 1024u;
;     const int aoff = lds_byte(wr * 64 + fr, fq * 8), boff = lds_byte(wc * 32 + fr, fq * 8);
;     ...
;     Unit cur, nxt; int ui = 0;
;     if (!S.next(0, cur)) return;
;     f32x4 acc[2][2][4][2];
; #pragma unroll
;     for (int a = 0; a < 2; ++a)
; #pragma unroll
;         for (int b = 0; b < 2; ++b)
; #pragma unroll
;             for (int m = 0; m < 4; ++m)
; #pragma unroll
;                 for (int n = 0; n < 2; ++n) acc[a][b][m][n] = (f32x4){0.f, 0.f, 0.f, 0.f};
;     bf16x8 At[4][2], B0[2][2], B1[2][2];
;     const char* cA = (const char*)g.A + (size_t)cur.pm * tstep; const char* cB = (const char*)g.Bt + (size_t)cur.pn * tstep;
;     S.a_ready(cur);
;     if constexpr (SP2) {
;         PG8_STAGE(PG8_SB(0, 0), cB, voffB); PG8_STAGE(PG8_SB(0, 1), cB + hstep, voffB); PG8_STAGE(PG8_SA(0, 0), cA, voffA); PG8_STAGE(PG8_SA(0, 1), cA + hstep, voffA);
;         if (wr == 1) PG8_BAR;
;         PG8_WAIT_V(2); PG8_BAR;
; __global__ void __launch_bounds__(NTHR, 2) mega_fwd(Args args) {
;     ...
;         pg8::Gemm g{XN, W1, T, FF, DM}; pg8::StaticOrder S; S.init(T, FF, G, bx, WGM_P9);
;         pg8::EpiRelu2 E{HB, FF};
;         pg8::gemm_phase<pg8::EpiRelu2, pg8::StaticOrder, true, true>(L, g, S, E);
.LBB0_762:
	s_or_b64 exec, exec, s[12:13]
	s_nop 0
	s_nop 0
	s_nop 0
	s_nop 0
	s_nop 0
	s_nop 0
	s_nop 0
	s_nop 0
	s_nop 0
	s_nop 0
	s_mov_b64 s[14:15], s[0:1]
	s_mov_b64 s[16:17], s[0:1]
	s_mov_b64 s[12:13], s[0:1]
	v_mov_b32_e32 v14, v216
	s_waitcnt lgkmcnt(0)
	s_barrier
	s_cmpk_lt_i32 s2, 0x1000
	s_nop 0
	v_readfirstlane_b32 s18, v14
	s_cbranch_scc0 .LBB0_782
	v_lshlrev_b32_e32 v0, 4, v14
	v_add_u32_e32 v1, 0x2000, v0
	v_ashrrev_i32_e32 v2, 31, v1
	v_lshrrev_b32_e32 v2, 22, v2
	v_add_u32_e32 v2, v1, v2
	v_ashrrev_i32_e32 v8, 10, v2
	v_mul_i32_i24_e32 v2, 0x400, v8
	v_sub_u32_e32 v1, v1, v2
	v_lshrrev_b32_e32 v2, 4, v1
	v_bitop3_b32 v1, v2, v1, 32 bitop3:0x6c
	v_ashrrev_i32_e32 v2, 31, v1
	s_load_dwordx2 s[14:15], s[14:15], 0xc8
	s_nop 0
	s_load_dwordx2 s[16:17], s[16:17], 0xc8
	v_lshrrev_b32_e32 v2, 26, v2
	v_add_u32_e32 v2, v1, v2
	v_lshlrev_b32_e32 v3, 3, v8
	v_ashrrev_i32_e32 v9, 6, v2
	v_and_b32_e32 v3, -16, v3
	v_add_u32_e32 v3, v9, v3
	s_waitcnt lgkmcnt(0)
	s_add_u32 s40, s14, 0x7800000
	v_and_b32_e32 v4, 3, v9
	s_mov_b32 s14, 0xfffe0
	v_lshrrev_b32_e32 v5, 2, v3
	v_lshlrev_b32_e32 v6, 1, v3
	v_and_b32_e32 v2, 0xc0, v2
	v_and_or_b32 v4, v3, s14, v4
	v_and_b32_e32 v5, 4, v5
	v_and_b32_e32 v6, 24, v6
	v_sub_u32_e32 v1, v1, v2
	v_mov_b32_e32 v2, 1
	v_or3_b32 v4, v4, v5, v6
	v_lshlrev_b32_e32 v5, 5, v8
	v_ashrrev_i16_sdwa v1, v2, sext(v1) dst_sel:DWORD dst_unused:UNUSED_PAD src0_sel:DWORD src1_sel:BYTE_0
	v_and_b32_e32 v5, 32, v5
	v_bfe_i32 v10, v1, 0, 16
	v_add_lshl_u32 v1, v5, v10, 1
	s_waitcnt vmcnt(0)
	v_lshl_add_u32 v128, v4, 12, v1
	v_lshl_add_u32 v130, v3, 12, v1
	v_bfe_i32 v1, v14, 27, 1
	v_lshrrev_b32_e32 v1, 22, v1
	v_add_u32_e32 v1, v0, v1
	v_and_b32_e32 v1, 0xfffffc00, v1
	v_sub_u32_e32 v0, v0, v1
	v_lshrrev_b32_e32 v1, 4, v0
	v_ashrrev_i32_e32 v3, 31, v14
	v_bitop3_b32 v0, v1, v0, 32 bitop3:0x6c
	v_lshrrev_b32_e32 v3, 26, v3
	v_ashrrev_i32_e32 v1, 31, v0
	v_add_u32_e32 v3, v14, v3
	s_addc_u32 s41, s15, 0
	v_lshrrev_b32_e32 v1, 26, v1
	v_ashrrev_i32_e32 v12, 6, v3
	s_add_u32 s44, s16, 0x3600000
	v_add_u32_e32 v1, v0, v1
	v_lshlrev_b32_e32 v3, 3, v12
	s_addc_u32 s45, s17, 0
	s_ashr_i32 s19, s18, 6
	v_ashrrev_i32_e32 v11, 6, v1
	v_and_b32_e32 v3, -16, v3
	s_ashr_i32 s20, s18, 8
	s_lshl_b32 s47, s19, 10
	v_add_u32_e32 v3, v11, v3
	v_and_b32_e32 v4, 3, v11
	s_lshl_b32 s17, s59, 9
	v_and_or_b32 v4, v3, s14, v4
	s_mul_i32 s16, s59, 0x201
	s_and_b64 s[14:15], s[42:43], exec
	s_cselect_b32 s14, s16, s17
	s_add_i32 s14, s14, s56
	s_ashr_i32 s15, s14, 31
	s_lshr_b32 s15, s15, 24
	s_add_i32 s15, s14, s15
	s_ashr_i32 s16, s15, 8
	s_and_b32 s15, s15, 0xff00
	s_sub_i32 s15, s14, s15
	s_sext_i32_i16 s14, s15
	s_bfe_u32 s14, s14, 0x3001c
	s_add_i32 s17, s15, s14
	s_sext_i32_i16 s14, s17
	s_and_b32 s17, s17, 0xfff8
	s_sub_i32 s15, s15, s17
	s_lshl_b32 s16, s16, 3
	s_sext_i32_i16 s15, s15
	v_lshrrev_b32_e32 v5, 2, v3
	v_lshlrev_b32_e32 v6, 1, v3
	v_and_b32_e32 v1, 0xc0, v1
	s_lshr_b32 s14, s14, 3
	s_add_i32 s28, s16, s15
	v_and_b32_e32 v5, 4, v5
	v_and_b32_e32 v6, 24, v6
	v_sub_u32_e32 v0, v0, v1
	s_ashr_i32 s29, s28, 31
	s_bfe_i64 s[22:23], s[14:15], 0x100000
	v_or3_b32 v4, v4, v5, v6
	v_lshlrev_b32_e32 v5, 5, v12
	v_ashrrev_i16_sdwa v0, v2, sext(v0) dst_sel:DWORD dst_unused:UNUSED_PAD src0_sel:DWORD src1_sel:BYTE_0
	s_lshl_b64 s[16:17], s[28:29], 20
	s_lshl_b64 s[22:23], s[22:23], 20
	v_and_b32_e32 v5, 32, v5
	v_bfe_i32 v13, v0, 0, 16
	s_add_u32 s34, s44, s22
	v_add_lshl_u32 v0, v5, v13, 1
	s_addc_u32 s35, s45, s23
	s_add_i32 s50, s47, 0
	v_lshl_add_u32 v132, v4, 12, v0
	s_add_i32 m0, s50, 0x10000
	v_lshl_add_u32 v134, v3, 12, v0
	global_load_lds_dwordx4 v132, s[34:35]
	s_add_i32 m0, s50, 0x12000
	s_add_u32 s22, s34, 0x80000
	global_load_lds_dwordx4 v128, s[34:35]
	s_addc_u32 s23, s35, 0
	s_add_i32 m0, s50, 0x14000
	v_mov_b32_e32 v133, 0
	global_load_lds_dwordx4 v132, s[22:23]
	s_add_i32 m0, s50, 0x16000
	s_add_u32 s30, s40, s16
	s_addc_u32 s31, s41, s17
	s_add_i32 s51, s50, 0x2000
	global_load_lds_dwordx4 v128, s[22:23]
	s_mov_b32 m0, s50
	s_add_u32 s16, s30, 0x80000
	global_load_lds_dwordx4 v134, s[30:31]
	s_mov_b32 m0, s51
	s_addc_u32 s17, s31, 0
	s_add_i32 s52, s50, 0x4000
	global_load_lds_dwordx4 v130, s[30:31]
	s_mov_b32 m0, s52
	s_add_i32 s53, s50, 0x6000
	global_load_lds_dwordx4 v134, s[16:17]
	s_mov_b32 m0, s53
	v_mov_b32_e32 v129, v133
	global_load_lds_dwordx4 v130, s[16:17]
	s_load_dwordx2 s[16:17], s[12:13], 0xc8
	v_mov_b32_e32 v135, v133
	v_mov_b32_e32 v131, v133
	s_cmp_eq_u32 s20, 1
	s_mov_b32 s54, 0
	v_lshl_add_u64 v[6:7], s[34:35], 0, v[132:133]
	v_lshl_add_u64 v[4:5], s[34:35], 0, v[128:129]
	v_lshl_add_u64 v[0:1], s[30:31], 0, v[134:135]
	s_cselect_b64 s[12:13], -1, 0
	s_cmp_lg_u32 s20, 1
	v_lshl_add_u64 v[2:3], s[30:31], 0, v[130:131]
	s_cbranch_scc1 .LBB0_765
	s_barrier
